# attention row sums accumulated with packed f32 adds (two partial-sum pairs), order of the f32 row-sum changed
# baseline (speedup 1.0000x reference)
.Latt1_noload_a:
	ds_read_b128 v[242:245], v250 offset:13888
	v_exp_f32_e32 v88, v88
	v_exp_f32_e32 v89, v89
	v_exp_f32_e32 v90, v90
	s_waitcnt lgkmcnt(10)
	v_mfma_f32_32x32x16_bf16 v[32:47], v[192:195], v[80:83], v[32:47]
	ds_read_b128 v[246:249], v250 offset:96
	v_exp_f32_e32 v91, v91
	v_exp_f32_e32 v92, v92
	v_exp_f32_e32 v93, v93
	v_pk_add_f32 v[84:85], v[84:85], v[88:89]
	s_waitcnt lgkmcnt(10)
	v_mfma_f32_32x32x16_bf16 v[16:31], v[196:199], v[80:83], v[16:31]
	ds_read_b128 v[180:183], v250 offset:4704
	v_exp_f32_e32 v94, v94
	v_exp_f32_e32 v95, v95
	v_pk_add_f32 v[150:151], v[150:151], v[90:91]
	v_pk_add_f32 v[84:85], v[84:85], v[92:93]
	s_waitcnt lgkmcnt(10)
	v_mfma_f32_32x32x16_bf16 v[0:15], v[200:203], v[80:83], v[0:15]
	ds_read_b128 v[184:187], v250 offset:9312
	v_cvt_pk_bf16_f32 v88, v88, v89
	v_cvt_pk_bf16_f32 v89, v90, v91
	v_cvt_pk_bf16_f32 v90, v92, v93
	v_cvt_pk_bf16_f32 v91, v94, v95
	v_pk_add_f32 v[150:151], v[150:151], v[94:95]
	s_waitcnt lgkmcnt(10)
	v_mfma_f32_32x32x16_bf16 v[48:63], v[204:207], v[88:91], v[48:63]
	ds_read_b128 v[188:191], v250 offset:13920
	v_exp_f32_e32 v96, v96
	v_exp_f32_e32 v97, v97
	v_exp_f32_e32 v98, v98
	s_waitcnt lgkmcnt(10)
	v_mfma_f32_32x32x16_bf16 v[32:47], v[218:221], v[88:91], v[32:47]
	v_exp_f32_e32 v99, v99
	v_exp_f32_e32 v100, v100
	v_exp_f32_e32 v101, v101
	v_pk_add_f32 v[84:85], v[84:85], v[96:97]
	s_waitcnt lgkmcnt(9)
	v_mfma_f32_32x32x16_bf16 v[16:31], v[222:225], v[88:91], v[16:31]
	v_exp_f32_e32 v102, v102
	v_exp_f32_e32 v103, v103
	v_pk_add_f32 v[150:151], v[150:151], v[98:99]
	v_pk_add_f32 v[84:85], v[84:85], v[100:101]
	s_waitcnt lgkmcnt(8)
	v_mfma_f32_32x32x16_bf16 v[0:15], v[226:229], v[88:91], v[0:15]
	v_cvt_pk_bf16_f32 v96, v96, v97
	v_cvt_pk_bf16_f32 v97, v98, v99
	v_cvt_pk_bf16_f32 v98, v100, v101
	v_cvt_pk_bf16_f32 v99, v102, v103
	v_pk_add_f32 v[150:151], v[150:151], v[102:103]
	s_barrier
	ds_read_b128 v[192:195], v173
	ds_read_b128 v[196:199], v173 offset:8704
	ds_read_b128 v[200:203], v173 offset:32
	ds_read_b128 v[204:207], v173 offset:8736
	ds_read_b128 v[218:221], v173 offset:64
	ds_read_b128 v[222:225], v173 offset:8768
	ds_read_b128 v[226:229], v173 offset:96
	s_waitcnt lgkmcnt(14)
	v_mfma_f32_32x32x16_bf16 v[48:63], v[230:233], v[96:99], v[48:63]
	ds_read_b128 v[230:233], v173 offset:8800
	v_exp_f32_e32 v104, v104
	v_exp_f32_e32 v105, v105
	v_exp_f32_e32 v106, v106
	s_waitcnt lgkmcnt(14)
	v_mfma_f32_32x32x16_bf16 v[32:47], v[234:237], v[96:99], v[32:47]
	v_exp_f32_e32 v107, v107
	v_exp_f32_e32 v108, v108
	v_exp_f32_e32 v109, v109
	v_pk_add_f32 v[84:85], v[84:85], v[104:105]
	s_waitcnt lgkmcnt(13)
	v_mfma_f32_32x32x16_bf16 v[16:31], v[238:241], v[96:99], v[16:31]
	v_exp_f32_e32 v110, v110
	v_exp_f32_e32 v111, v111
	v_pk_add_f32 v[150:151], v[150:151], v[106:107]
	v_pk_add_f32 v[84:85], v[84:85], v[108:109]
	s_waitcnt lgkmcnt(12)
	v_mfma_f32_32x32x16_bf16 v[0:15], v[242:245], v[96:99], v[0:15]
	v_cvt_pk_bf16_f32 v104, v104, v105
	v_cvt_pk_bf16_f32 v105, v106, v107
	v_cvt_pk_bf16_f32 v106, v108, v109
	v_cvt_pk_bf16_f32 v107, v110, v111
	v_pk_add_f32 v[150:151], v[150:151], v[110:111]
	s_waitcnt lgkmcnt(11)
	v_mfma_f32_32x32x16_bf16 v[48:63], v[246:249], v[104:107], v[48:63]
	v_pk_add_f32 v[84:85], v[84:85], v[150:151]
	s_waitcnt lgkmcnt(10)
	v_mfma_f32_32x32x16_bf16 v[32:47], v[180:183], v[104:107], v[32:47]
	s_waitcnt lgkmcnt(9)
	v_mfma_f32_32x32x16_bf16 v[16:31], v[184:187], v[104:107], v[16:31]
	v_add_f32_e32 v84, v84, v85
	s_waitcnt lgkmcnt(8)
	v_mfma_f32_32x32x16_bf16 v[0:15], v[188:191], v[104:107], v[0:15]
	v_add_f32_e32 v158, v158, v84
	s_branch .Latt1_qk

; #define ATT_PV(bufv) do { \
;         const LAS bf16* Vb = (const LAS bf16*)(lds + 3 * KBYTES + (bufv) * VBYTES) + hi * 8; \
;         _Pragma("unroll") for (int es = 0; es < 4; ++es) _Pragma("unroll") for (int kk = 0; kk < 4; ++kk) { \
;             const bf16x8 a = *(const LAS bf16x8*)(Vb + (es * 32 + r32) * VP + kk * 16); O[es] = MFMA32(a, pf[kk], O[es]); } } while (0)
; DI void attn_unit(LAS unsigned char* lds, int tid, const bf16* __restrict__ P, const bf16* __restrict__ Vt, bf16* MG, int b, int h, int qrow0, int jt0, int jt1,
;                   float lam, float oscale, const float* subg) {
;     ...
;     if (halfB) { ATT_PV(pbuf); }
.Latt1_nors:
	v_exp_f32_e32 v80, v80
	v_exp_f32_e32 v81, v81
	v_exp_f32_e32 v82, v82
	v_exp_f32_e32 v83, v83
	v_exp_f32_e32 v84, v84
	v_exp_f32_e32 v85, v85
	v_exp_f32_e32 v86, v86
	v_exp_f32_e32 v87, v87
	v_pk_add_f32 v[150:151], v[80:81], v[82:83]
	v_cvt_pk_bf16_f32 v80, v80, v81
	v_cvt_pk_bf16_f32 v81, v82, v83
	v_cvt_pk_bf16_f32 v82, v84, v85
	v_cvt_pk_bf16_f32 v83, v86, v87
	v_pk_add_f32 v[84:85], v[84:85], v[86:87]
	s_cmpk_eq_i32 s17, 0x10c0
	s_cbranch_scc1 .LBB0_312
	s_mov_b32 s21, s19
	s_branch .LBB0_300
.LBB0_312:
	s_and_saveexec_b64 s[2:3], s[0:1]
	s_cbranch_execz .LBB0_314
	s_mul_i32 s22, s19, 0x4800
	s_add_i32 s22, s22, 0xcc00
	v_add_u32_e32 v250, s22, v178
	ds_read_b128 v[188:191], v250
	ds_read_b128 v[192:195], v250 offset:4608
	ds_read_b128 v[196:199], v250 offset:9216
	ds_read_b128 v[200:203], v250 offset:13824
	ds_read_b128 v[204:207], v250 offset:32
	ds_read_b128 v[218:221], v250 offset:4640
	ds_read_b128 v[222:225], v250 offset:9248
	ds_read_b128 v[226:229], v250 offset:13856
	ds_read_b128 v[230:233], v250 offset:64
	ds_read_b128 v[234:237], v250 offset:4672
	ds_read_b128 v[238:241], v250 offset:9280
	ds_read_b128 v[242:245], v250 offset:13888
	ds_read_b128 v[246:249], v250 offset:96
	ds_read_b128 v[180:183], v250 offset:4704
	ds_read_b128 v[184:187], v250 offset:9312
	s_waitcnt lgkmcnt(14)
	v_mfma_f32_32x32x16_bf16 v[48:63], v[188:191], v[80:83], v[48:63]
	ds_read_b128 v[188:191], v250 offset:13920
	v_exp_f32_e32 v88, v88
	v_exp_f32_e32 v89, v89
	v_exp_f32_e32 v90, v90
	s_waitcnt lgkmcnt(14)
	v_mfma_f32_32x32x16_bf16 v[32:47], v[192:195], v[80:83], v[32:47]
	v_exp_f32_e32 v91, v91
	v_exp_f32_e32 v92, v92
	v_exp_f32_e32 v93, v93
	v_pk_add_f32 v[84:85], v[84:85], v[88:89]
	s_waitcnt lgkmcnt(13)
	v_mfma_f32_32x32x16_bf16 v[16:31], v[196:199], v[80:83], v[16:31]
	v_exp_f32_e32 v94, v94
	v_exp_f32_e32 v95, v95
	v_pk_add_f32 v[150:151], v[150:151], v[90:91]
	v_pk_add_f32 v[84:85], v[84:85], v[92:93]
	s_waitcnt lgkmcnt(12)
	v_mfma_f32_32x32x16_bf16 v[0:15], v[200:203], v[80:83], v[0:15]
	v_cvt_pk_bf16_f32 v88, v88, v89
	v_cvt_pk_bf16_f32 v89, v90, v91
	v_cvt_pk_bf16_f32 v90, v92, v93
	v_cvt_pk_bf16_f32 v91, v94, v95
	v_pk_add_f32 v[150:151], v[150:151], v[94:95]
	s_waitcnt lgkmcnt(11)
	v_mfma_f32_32x32x16_bf16 v[48:63], v[204:207], v[88:91], v[48:63]
	v_exp_f32_e32 v96, v96
	v_exp_f32_e32 v97, v97
	v_exp_f32_e32 v98, v98
	s_waitcnt lgkmcnt(10)
	v_mfma_f32_32x32x16_bf16 v[32:47], v[218:221], v[88:91], v[32:47]
	v_exp_f32_e32 v99, v99
	v_exp_f32_e32 v100, v100
	v_exp_f32_e32 v101, v101
	v_pk_add_f32 v[84:85], v[84:85], v[96:97]
	s_waitcnt lgkmcnt(9)
	v_mfma_f32_32x32x16_bf16 v[16:31], v[222:225], v[88:91], v[16:31]
	v_exp_f32_e32 v102, v102
	v_exp_f32_e32 v103, v103
	v_pk_add_f32 v[150:151], v[150:151], v[98:99]
	v_pk_add_f32 v[84:85], v[84:85], v[100:101]
	s_waitcnt lgkmcnt(8)
	v_mfma_f32_32x32x16_bf16 v[0:15], v[226:229], v[88:91], v[0:15]
	v_cvt_pk_bf16_f32 v96, v96, v97
	v_cvt_pk_bf16_f32 v97, v98, v99
	v_cvt_pk_bf16_f32 v98, v100, v101
	v_cvt_pk_bf16_f32 v99, v102, v103
	v_pk_add_f32 v[150:151], v[150:151], v[102:103]
	s_waitcnt lgkmcnt(7)
	v_mfma_f32_32x32x16_bf16 v[48:63], v[230:233], v[96:99], v[48:63]
	v_exp_f32_e32 v104, v104
	v_exp_f32_e32 v105, v105
	v_exp_f32_e32 v106, v106
	s_waitcnt lgkmcnt(6)
	v_mfma_f32_32x32x16_bf16 v[32:47], v[234:237], v[96:99], v[32:47]
	v_exp_f32_e32 v107, v107
	v_exp_f32_e32 v108, v108
	v_exp_f32_e32 v109, v109
	v_pk_add_f32 v[84:85], v[84:85], v[104:105]
	s_waitcnt lgkmcnt(5)
	v_mfma_f32_32x32x16_bf16 v[16:31], v[238:241], v[96:99], v[16:31]
	v_exp_f32_e32 v110, v110
	v_exp_f32_e32 v111, v111
	v_pk_add_f32 v[150:151], v[150:151], v[106:107]
	v_pk_add_f32 v[84:85], v[84:85], v[108:109]
	s_waitcnt lgkmcnt(4)
	v_mfma_f32_32x32x16_bf16 v[0:15], v[242:245], v[96:99], v[0:15]
	v_cvt_pk_bf16_f32 v104, v104, v105
	v_cvt_pk_bf16_f32 v105, v106, v107
	v_cvt_pk_bf16_f32 v106, v108, v109
	v_cvt_pk_bf16_f32 v107, v110, v111
	v_pk_add_f32 v[150:151], v[150:151], v[110:111]
	s_waitcnt lgkmcnt(3)
	v_mfma_f32_32x32x16_bf16 v[48:63], v[246:249], v[104:107], v[48:63]
	v_pk_add_f32 v[84:85], v[84:85], v[150:151]
	s_waitcnt lgkmcnt(2)
	v_mfma_f32_32x32x16_bf16 v[32:47], v[180:183], v[104:107], v[32:47]
	s_waitcnt lgkmcnt(1)
	v_mfma_f32_32x32x16_bf16 v[16:31], v[184:187], v[104:107], v[16:31]
	v_add_f32_e32 v84, v84, v85
	s_waitcnt lgkmcnt(0)
	v_mfma_f32_32x32x16_bf16 v[0:15], v[188:191], v[104:107], v[0:15]
	v_add_f32_e32 v158, v158, v84
